# conv phase set-up: 14 weight tap groups loaded five in flight (rotating destination register sets) instead of one round trip per group
# speedup vs baseline: 1.0073x; 1.0016x over previous
; DI void phase_conv(const Params& p, LAS unsigned char* lds) {
;     ...
;     unsigned wp[16][8];
; #pragma unroll
;     for (int i = 0; i < 16; ++i) {
;         const int ja = par ? 2 * i - 1 : 2 * i, jb = ja + 1;
;         f32x4 a0 = (f32x4){0.f, 0.f, 0.f, 0.f}, a1 = a0, b0 = a0, b1 = a0;
;         if (ja >= 0) { a0 = *(const f32x4*)(caw + ja * MW + c0); a1 = *(const f32x4*)(caw + ja * MW + c0 + 4); }
;         if (jb <= 30) { b0 = *(const f32x4*)(caw + jb * MW + c0); b1 = *(const f32x4*)(caw + jb * MW + c0 + 4); }
; #pragma unroll
;         for (int k = 0; k < 4; ++k) { asm volatile("v_cvt_pk_bf16_f32 %0, %1, %2" : "=v"(wp[i][k]) : "v"(a0[k]), "v"(b0[k])); asm volatile("v_cvt_pk_bf16_f32 %0, %1, %2" : "=v"(wp[i][4 + k]) : "v"(a1[k]), "v"(b1[k])); }
;     }
.LBB0_408:
	v_cndmask_b32_e64 v1, 0, -1, s[0:1]
	v_lshlrev_b32_e32 v18, 2, v20
	v_readfirstlane_b32 s7, v1
	s_lshl_b32 s76, s7, 9
	s_ashr_i32 s77, s76, 31
	s_lshl_b64 s[76:77], s[76:77], 2
	s_add_u32 s76, s52, s76
	s_addc_u32 s77, s53, s77
	global_load_dwordx4 v[12:15], v18, s[76:77] offset:2048
	global_load_dwordx4 v[22:25], v18, s[76:77] offset:2064
	s_mov_b32 s51, 0
	s_lshl_b32 s50, s50, 2
	v_lshl_add_u64 v[16:17], v[10:11], 0, s[50:51]
	s_add_u32 s76, s52, s50
	s_addc_u32 s77, s53, 0
	s_lshl_b32 s50, s78, 2
	s_waitcnt vmcnt(1)
	v_cvt_pk_bf16_f32 v1, v6, v12
	s_waitcnt vmcnt(0)
	v_cvt_pk_bf16_f32 v52, v2, v22
	v_cvt_pk_bf16_f32 v53, v7, v13
	v_cvt_pk_bf16_f32 v54, v3, v23
	v_cvt_pk_bf16_f32 v55, v8, v14
	v_cvt_pk_bf16_f32 v56, v4, v24
	v_cvt_pk_bf16_f32 v57, v9, v15
	v_cvt_pk_bf16_f32 v58, v5, v25
	global_load_dwordx4 v[2:5], v[16:17], off offset:16
	global_load_dwordx4 v[6:9], v[16:17], off
	global_load_dwordx4 v[12:15], v18, s[76:77] offset:2048
	global_load_dwordx4 v[22:25], v18, s[76:77] offset:2064
	v_lshl_add_u64 v[16:17], v[10:11], 0, s[50:51]
	s_add_u32 s76, s52, s50
	s_addc_u32 s77, s53, 0
	s_lshl_b32 s50, s72, 2
	s_add_u32 s72, s52, s50
	s_addc_u32 s73, s53, 0
	global_load_dwordx4 v[216:219], v[16:17], off offset:16
	global_load_dwordx4 v[220:223], v[16:17], off
	global_load_dwordx4 v[224:227], v18, s[76:77] offset:2048
	global_load_dwordx4 v[228:231], v18, s[76:77] offset:2064
	v_lshl_add_u64 v[16:17], v[10:11], 0, s[50:51]
	s_lshl_b32 s50, s70, 2
	s_add_u32 s70, s52, s50
	s_addc_u32 s71, s53, 0
	global_load_dwordx4 v[232:235], v[16:17], off offset:16
	global_load_dwordx4 v[236:239], v[16:17], off
	global_load_dwordx4 v[240:243], v18, s[72:73] offset:2048
	global_load_dwordx4 v[248:251], v18, s[72:73] offset:2064
	v_lshl_add_u64 v[16:17], v[10:11], 0, s[50:51]
	s_lshl_b32 s50, s68, 2
	s_add_u32 s68, s52, s50
	s_addc_u32 s69, s53, 0
	global_load_dwordx4 v[180:183], v[16:17], off offset:16
	global_load_dwordx4 v[184:187], v[16:17], off
	global_load_dwordx4 v[188:191], v18, s[70:71] offset:2048
	global_load_dwordx4 v[192:195], v18, s[70:71] offset:2064
	v_lshl_add_u64 v[16:17], v[10:11], 0, s[50:51]
	s_lshl_b32 s50, s66, 2
	s_add_u32 s66, s52, s50
	s_addc_u32 s67, s53, 0
	global_load_dwordx4 v[198:201], v[16:17], off offset:16
	global_load_dwordx4 v[202:205], v[16:17], off
	global_load_dwordx4 v[208:211], v18, s[68:69] offset:2048
	global_load_dwordx4 v[212:215], v18, s[68:69] offset:2064
	v_lshl_add_u64 v[16:17], v[10:11], 0, s[50:51]
	s_lshl_b32 s50, s64, 2
	s_add_u32 s64, s52, s50
	s_addc_u32 s65, s53, 0
	s_waitcnt vmcnt(16)
	v_cvt_pk_bf16_f32 v59, v6, v12
	v_cvt_pk_bf16_f32 v60, v2, v22
	v_cvt_pk_bf16_f32 v61, v7, v13
	v_cvt_pk_bf16_f32 v62, v3, v23
	v_cvt_pk_bf16_f32 v63, v8, v14
	v_cvt_pk_bf16_f32 v64, v4, v24
	v_cvt_pk_bf16_f32 v65, v9, v15
	v_cvt_pk_bf16_f32 v66, v5, v25
	global_load_dwordx4 v[2:5], v[16:17], off offset:16
	global_load_dwordx4 v[6:9], v[16:17], off
	global_load_dwordx4 v[12:15], v18, s[66:67] offset:2048
	global_load_dwordx4 v[22:25], v18, s[66:67] offset:2064
	v_lshl_add_u64 v[16:17], v[10:11], 0, s[50:51]
	s_lshl_b32 s50, s62, 2
	s_add_u32 s62, s52, s50
	s_addc_u32 s63, s53, 0
	s_waitcnt vmcnt(16)
	v_cvt_pk_bf16_f32 v67, v220, v224
	v_cvt_pk_bf16_f32 v68, v216, v228
	v_cvt_pk_bf16_f32 v69, v221, v225
	v_cvt_pk_bf16_f32 v70, v217, v229
	v_cvt_pk_bf16_f32 v71, v222, v226
	v_cvt_pk_bf16_f32 v72, v218, v230
	v_cvt_pk_bf16_f32 v73, v223, v227
	v_cvt_pk_bf16_f32 v74, v219, v231
	global_load_dwordx4 v[216:219], v[16:17], off offset:16
	global_load_dwordx4 v[220:223], v[16:17], off
	global_load_dwordx4 v[224:227], v18, s[64:65] offset:2048
	global_load_dwordx4 v[228:231], v18, s[64:65] offset:2064
	v_lshl_add_u64 v[16:17], v[10:11], 0, s[50:51]
	s_lshl_b32 s50, s60, 2
	s_add_u32 s60, s52, s50
	s_addc_u32 s61, s53, 0
	s_waitcnt vmcnt(16)
	v_cvt_pk_bf16_f32 v75, v236, v240
	v_cvt_pk_bf16_f32 v76, v232, v248
	v_cvt_pk_bf16_f32 v77, v237, v241
	v_cvt_pk_bf16_f32 v78, v233, v249
	v_cvt_pk_bf16_f32 v79, v238, v242
	v_cvt_pk_bf16_f32 v80, v234, v250
	v_cvt_pk_bf16_f32 v81, v239, v243
	v_cvt_pk_bf16_f32 v82, v235, v251
	global_load_dwordx4 v[232:235], v[16:17], off offset:16
	global_load_dwordx4 v[236:239], v[16:17], off
	global_load_dwordx4 v[240:243], v18, s[62:63] offset:2048
	global_load_dwordx4 v[248:251], v18, s[62:63] offset:2064
	v_lshl_add_u64 v[16:17], v[10:11], 0, s[50:51]
	s_lshl_b32 s50, s58, 2
	s_add_u32 s58, s52, s50
	s_addc_u32 s59, s53, 0
	s_waitcnt vmcnt(16)
	v_cvt_pk_bf16_f32 v83, v184, v188
	v_cvt_pk_bf16_f32 v84, v180, v192
	v_cvt_pk_bf16_f32 v85, v185, v189
	v_cvt_pk_bf16_f32 v86, v181, v193
	v_cvt_pk_bf16_f32 v87, v186, v190
	v_cvt_pk_bf16_f32 v88, v182, v194
	v_cvt_pk_bf16_f32 v89, v187, v191
	v_cvt_pk_bf16_f32 v90, v183, v195
	global_load_dwordx4 v[180:183], v[16:17], off offset:16
	global_load_dwordx4 v[184:187], v[16:17], off
	global_load_dwordx4 v[188:191], v18, s[60:61] offset:2048
	global_load_dwordx4 v[192:195], v18, s[60:61] offset:2064
	v_lshl_add_u64 v[16:17], v[10:11], 0, s[50:51]
	s_lshl_b32 s50, s56, 2
	s_add_u32 s56, s52, s50
	s_addc_u32 s57, s53, 0
	s_waitcnt vmcnt(16)
; DI void phase_conv(const Params& p, LAS unsigned char* lds) {
;     ...
;     unsigned wp[16][8];
; #pragma unroll
;     for (int i = 0; i < 16; ++i) {
;         const int ja = par ? 2 * i - 1 : 2 * i, jb = ja + 1;
;         f32x4 a0 = (f32x4){0.f, 0.f, 0.f, 0.f}, a1 = a0, b0 = a0, b1 = a0;
;         if (ja >= 0) { a0 = *(const f32x4*)(caw + ja * MW + c0); a1 = *(const f32x4*)(caw + ja * MW + c0 + 4); }
;         if (jb <= 30) { b0 = *(const f32x4*)(caw + jb * MW + c0); b1 = *(const f32x4*)(caw + jb * MW + c0 + 4); }
; #pragma unroll
;         for (int k = 0; k < 4; ++k) { asm volatile("v_cvt_pk_bf16_f32 %0, %1, %2" : "=v"(wp[i][k]) : "v"(a0[k]), "v"(b0[k])); asm volatile("v_cvt_pk_bf16_f32 %0, %1, %2" : "=v"(wp[i][4 + k]) : "v"(a1[k]), "v"(b1[k])); }
;     }
	v_cvt_pk_bf16_f32 v91, v202, v208
	v_cvt_pk_bf16_f32 v92, v198, v212
	v_cvt_pk_bf16_f32 v93, v203, v209
	v_cvt_pk_bf16_f32 v94, v199, v213
	v_cvt_pk_bf16_f32 v95, v204, v210
	v_cvt_pk_bf16_f32 v96, v200, v214
	v_cvt_pk_bf16_f32 v97, v205, v211
	v_cvt_pk_bf16_f32 v98, v201, v215
	global_load_dwordx4 v[198:201], v[16:17], off offset:16
	global_load_dwordx4 v[202:205], v[16:17], off
	global_load_dwordx4 v[208:211], v18, s[58:59] offset:2048
	global_load_dwordx4 v[212:215], v18, s[58:59] offset:2064
	v_lshl_add_u64 v[16:17], v[10:11], 0, s[50:51]
	s_lshl_b32 s50, s54, 2
	s_add_u32 s54, s52, s50
	s_addc_u32 s55, s53, 0
	s_waitcnt vmcnt(16)
	v_cvt_pk_bf16_f32 v99, v6, v12
	v_cvt_pk_bf16_f32 v100, v2, v22
	v_cvt_pk_bf16_f32 v101, v7, v13
	v_cvt_pk_bf16_f32 v102, v3, v23
	v_cvt_pk_bf16_f32 v103, v8, v14
	v_cvt_pk_bf16_f32 v104, v4, v24
	v_cvt_pk_bf16_f32 v105, v9, v15
	v_cvt_pk_bf16_f32 v106, v5, v25
	global_load_dwordx4 v[2:5], v[16:17], off offset:16
	global_load_dwordx4 v[6:9], v[16:17], off
	global_load_dwordx4 v[12:15], v18, s[56:57] offset:2048
	global_load_dwordx4 v[22:25], v18, s[56:57] offset:2064
	v_lshl_add_u64 v[16:17], v[10:11], 0, s[50:51]
	s_waitcnt vmcnt(16)
	v_cvt_pk_bf16_f32 v107, v220, v224
	v_cvt_pk_bf16_f32 v108, v216, v228
	v_cvt_pk_bf16_f32 v109, v221, v225
	v_cvt_pk_bf16_f32 v110, v217, v229
	v_cvt_pk_bf16_f32 v111, v222, v226
	v_cvt_pk_bf16_f32 v112, v218, v230
	v_cvt_pk_bf16_f32 v113, v223, v227
	v_cvt_pk_bf16_f32 v114, v219, v231
	global_load_dwordx4 v[216:219], v[16:17], off offset:16
	global_load_dwordx4 v[220:223], v[16:17], off
	global_load_dwordx4 v[224:227], v18, s[54:55] offset:2048
	global_load_dwordx4 v[228:231], v18, s[54:55] offset:2064
	s_lshl_b32 s50, s10, 2
	v_lshl_add_u64 v[16:17], v[10:11], 0, s[50:51]
	s_add_u32 s10, s52, s50
	s_addc_u32 s11, s53, 0
	s_waitcnt vmcnt(16)
	v_cvt_pk_bf16_f32 v115, v236, v240
	v_cvt_pk_bf16_f32 v116, v232, v248
	v_cvt_pk_bf16_f32 v117, v237, v241
	v_cvt_pk_bf16_f32 v118, v233, v249
	v_cvt_pk_bf16_f32 v119, v238, v242
	v_cvt_pk_bf16_f32 v120, v234, v250
	v_cvt_pk_bf16_f32 v121, v239, v243
	v_cvt_pk_bf16_f32 v122, v235, v251
	global_load_dwordx4 v[232:235], v[16:17], off offset:16
	global_load_dwordx4 v[236:239], v[16:17], off
	global_load_dwordx4 v[240:243], v18, s[10:11] offset:2048
	global_load_dwordx4 v[248:251], v18, s[10:11] offset:2064
	s_lshl_b32 s50, s8, 2
	v_lshl_add_u64 v[16:17], v[10:11], 0, s[50:51]
	s_add_u32 s8, s52, s50
	s_addc_u32 s9, s53, 0
	s_waitcnt vmcnt(16)
	v_cvt_pk_bf16_f32 v123, v184, v188
	v_cvt_pk_bf16_f32 v124, v180, v192
	v_cvt_pk_bf16_f32 v125, v185, v189
	v_cvt_pk_bf16_f32 v126, v181, v193
	v_cvt_pk_bf16_f32 v127, v186, v190
	v_cvt_pk_bf16_f32 v128, v182, v194
	v_cvt_pk_bf16_f32 v129, v187, v191
	v_cvt_pk_bf16_f32 v130, v183, v195
	global_load_dwordx4 v[180:183], v[16:17], off offset:16
	global_load_dwordx4 v[184:187], v[16:17], off
	global_load_dwordx4 v[188:191], v18, s[8:9] offset:2048
	global_load_dwordx4 v[192:195], v18, s[8:9] offset:2064
	s_lshl_b32 s50, s6, 2
	v_lshl_add_u64 v[10:11], v[10:11], 0, s[50:51]
	s_waitcnt vmcnt(16)
	v_cvt_pk_bf16_f32 v131, v202, v208
	v_cvt_pk_bf16_f32 v132, v198, v212
	v_cvt_pk_bf16_f32 v133, v203, v209
	v_cvt_pk_bf16_f32 v134, v199, v213
	v_cvt_pk_bf16_f32 v135, v204, v210
	v_cvt_pk_bf16_f32 v136, v200, v214
	v_cvt_pk_bf16_f32 v137, v205, v211
	v_cvt_pk_bf16_f32 v138, v201, v215
	s_waitcnt vmcnt(12)
	v_cvt_pk_bf16_f32 v139, v6, v12
	v_cvt_pk_bf16_f32 v140, v2, v22
	v_cvt_pk_bf16_f32 v141, v7, v13
	v_cvt_pk_bf16_f32 v142, v3, v23
	v_cvt_pk_bf16_f32 v143, v8, v14
	v_cvt_pk_bf16_f32 v144, v4, v24
	v_cvt_pk_bf16_f32 v145, v9, v15
	v_cvt_pk_bf16_f32 v146, v5, v25
	s_waitcnt vmcnt(8)
	v_cvt_pk_bf16_f32 v147, v220, v224
	v_cvt_pk_bf16_f32 v148, v216, v228
	v_cvt_pk_bf16_f32 v149, v221, v225
	v_cvt_pk_bf16_f32 v150, v217, v229
	v_cvt_pk_bf16_f32 v151, v222, v226
	v_cvt_pk_bf16_f32 v152, v218, v230
	v_cvt_pk_bf16_f32 v153, v223, v227
	v_cvt_pk_bf16_f32 v154, v219, v231
	s_waitcnt vmcnt(4)
	v_cvt_pk_bf16_f32 v155, v236, v240
	v_cvt_pk_bf16_f32 v156, v232, v248
	v_cvt_pk_bf16_f32 v157, v237, v241
	v_cvt_pk_bf16_f32 v158, v233, v249
	v_cvt_pk_bf16_f32 v159, v238, v242
	v_cvt_pk_bf16_f32 v160, v234, v250
	v_cvt_pk_bf16_f32 v161, v239, v243
	v_cvt_pk_bf16_f32 v162, v235, v251
	s_waitcnt vmcnt(0)
	v_cvt_pk_bf16_f32 v163, v184, v188
	v_cvt_pk_bf16_f32 v164, v180, v192
	v_cvt_pk_bf16_f32 v165, v185, v189
	v_cvt_pk_bf16_f32 v166, v181, v193
	v_cvt_pk_bf16_f32 v167, v186, v190
	v_cvt_pk_bf16_f32 v168, v182, v194
	v_cvt_pk_bf16_f32 v169, v187, v191
	v_cvt_pk_bf16_f32 v170, v183, v195
	global_load_dwordx4 v[2:5], v[10:11], off offset:16
	global_load_dwordx4 v[6:9], v[10:11], off
	s_andn2_b64 vcc, exec, s[0:1]
	v_mov_b32_e32 v11, 0
	v_mov_b32_e32 v12, 0
	v_mov_b32_e32 v13, 0
	v_mov_b32_e32 v14, 0
	v_mov_b32_e32 v15, 0
	v_mov_b32_e32 v16, 0
	v_mov_b32_e32 v17, 0
	s_cbranch_vccnz .LBB0_410
	v_mov_b32_e32 v19, 0
	v_lshl_add_u64 v[10:11], s[52:53], 0, v[18:19]
	s_mov_b64 s[0:1], 0xf000
	v_add_co_u32_e32 v14, vcc, 0xf000, v10
	v_lshl_add_u64 v[12:13], v[10:11], 0, s[0:1]
	s_nop 0
	v_addc_co_u32_e32 v15, vcc, 0, v11, vcc
	global_load_dwordx4 v[10:13], v[12:13], off offset:16
	s_nop 0
	global_load_dwordx4 v[14:17], v[14:15], off
	s_waitcnt vmcnt(1)
	v_mov_b32_e32 v27, v10
